# k=6 weight conversion on workgroups 96+: the 16 row loads of a transpose trip issued together instead of pairwise with a drain after each pair
# speedup vs baseline: 1.0058x; 1.0058x over previous
; #define LAS __attribute__((address_space(3)))
; template <int MODE> __device__ __forceinline__ void transpose_item(const float* W, int K, int N, bf16_t* WT, LAS float* scr, int item, int lane) {
;     const int nblk = N / 32, kb = item / nblk, nb = item % nblk, k0 = 64 * kb, n0 = 32 * nb;
; #pragma unroll 8
;     for (int i = 0; i < 32; ++i) { const int kk = 2 * i + (lane >> 5); scr[kk * 33 + (lane & 31)] = W[(size_t)(k0 + kk) * N + n0 + (lane & 31)]; }
;     asm volatile("s_waitcnt lgkmcnt(0)" ::: "memory");
.LBB0_263:
	s_lshl_b32 s11, s6, 1
	s_lshl_b32 s10, s5, 1
	v_or_b32_e32 v18, s11, v0
	v_or_b32_e32 v20, s10, v7
	v_mad_i64_i32 v[18:19], s[98:99], v18, s13, v[10:11]
	v_mad_i64_i32 v[20:21], s[98:99], v20, s13, v[10:11]
	global_load_dword v44, v[18:19], off
	global_load_dword v45, v[20:21], off
	s_add_i32 s16, s11, 4
	s_add_i32 s14, s10, 4
	v_or_b32_e32 v18, s16, v0
	v_or_b32_e32 v20, s14, v7
	v_mad_i64_i32 v[18:19], s[98:99], v18, s13, v[10:11]
	v_mad_i64_i32 v[20:21], s[98:99], v20, s13, v[10:11]
	global_load_dword v46, v[18:19], off
	global_load_dword v47, v[20:21], off
	s_add_i32 s16, s11, 8
	s_add_i32 s14, s10, 8
	v_or_b32_e32 v18, s16, v0
	v_or_b32_e32 v20, s14, v7
	v_mad_i64_i32 v[18:19], s[98:99], v18, s13, v[10:11]
	v_mad_i64_i32 v[20:21], s[98:99], v20, s13, v[10:11]
	global_load_dword v48, v[18:19], off
	global_load_dword v49, v[20:21], off
	s_add_i32 s16, s11, 12
	s_add_i32 s14, s10, 12
	v_or_b32_e32 v18, s16, v0
	v_or_b32_e32 v20, s14, v7
	v_mad_i64_i32 v[18:19], s[98:99], v18, s13, v[10:11]
	v_mad_i64_i32 v[20:21], s[98:99], v20, s13, v[10:11]
	global_load_dword v50, v[18:19], off
	global_load_dword v51, v[20:21], off
	s_add_i32 s16, s11, 16
	s_add_i32 s14, s10, 16
	v_or_b32_e32 v18, s16, v0
	v_or_b32_e32 v20, s14, v7
	v_mad_i64_i32 v[18:19], s[98:99], v18, s13, v[10:11]
	v_mad_i64_i32 v[20:21], s[98:99], v20, s13, v[10:11]
	global_load_dword v52, v[18:19], off
	global_load_dword v53, v[20:21], off
	s_add_i32 s16, s11, 20
	s_add_i32 s14, s10, 20
	v_or_b32_e32 v18, s16, v0
	v_or_b32_e32 v20, s14, v7
	v_mad_i64_i32 v[18:19], s[98:99], v18, s13, v[10:11]
	v_mad_i64_i32 v[20:21], s[98:99], v20, s13, v[10:11]
	global_load_dword v54, v[18:19], off
	global_load_dword v55, v[20:21], off
	s_add_i32 s16, s11, 24
	s_add_i32 s14, s10, 24
	v_or_b32_e32 v18, s16, v0
	v_or_b32_e32 v20, s14, v7
	v_mad_i64_i32 v[18:19], s[98:99], v18, s13, v[10:11]
	v_mad_i64_i32 v[20:21], s[98:99], v20, s13, v[10:11]
	global_load_dword v56, v[18:19], off
	global_load_dword v57, v[20:21], off
	s_add_i32 s16, s11, 28
	s_add_i32 s14, s10, 28
	v_or_b32_e32 v18, s16, v0
	v_or_b32_e32 v20, s14, v7
	v_mad_i64_i32 v[18:19], s[98:99], v18, s13, v[10:11]
	v_mad_i64_i32 v[20:21], s[98:99], v20, s13, v[10:11]
	global_load_dword v58, v[18:19], off
	global_load_dword v59, v[20:21], off
	s_add_i32 s6, s6, 16
	s_add_i32 s5, s5, 16
	s_add_i32 s7, s7, -16
	v_or_b32_e32 v22, s11, v2
	v_or_b32_e32 v17, s10, v3
	v_mad_u64_u32 v[18:19], s[98:99], v22, s83, v[6:7]
	v_mad_u64_u32 v[20:21], s[98:99], v17, s83, v[6:7]
	s_waitcnt vmcnt(15)
	ds_write_b32 v18, v44
	s_waitcnt vmcnt(14)
	ds_write_b32 v20, v45
	s_add_i32 s16, s11, 4
	s_add_i32 s14, s10, 4
	v_or_b32_e32 v22, s16, v2
	v_or_b32_e32 v17, s14, v3
	v_mad_u64_u32 v[18:19], s[98:99], v22, s83, v[6:7]
	v_mad_u64_u32 v[20:21], s[98:99], v17, s83, v[6:7]
	s_waitcnt vmcnt(13)
	ds_write_b32 v18, v46
	s_waitcnt vmcnt(12)
	ds_write_b32 v20, v47
	s_add_i32 s16, s11, 8
	s_add_i32 s14, s10, 8
	v_or_b32_e32 v22, s16, v2
	v_or_b32_e32 v17, s14, v3
	v_mad_u64_u32 v[18:19], s[98:99], v22, s83, v[6:7]
	v_mad_u64_u32 v[20:21], s[98:99], v17, s83, v[6:7]
	s_waitcnt vmcnt(11)
	ds_write_b32 v18, v48
	s_waitcnt vmcnt(10)
	ds_write_b32 v20, v49
	s_add_i32 s16, s11, 12
	s_add_i32 s14, s10, 12
	v_or_b32_e32 v22, s16, v2
	v_or_b32_e32 v17, s14, v3
	v_mad_u64_u32 v[18:19], s[98:99], v22, s83, v[6:7]
	v_mad_u64_u32 v[20:21], s[98:99], v17, s83, v[6:7]
	s_waitcnt vmcnt(9)
	ds_write_b32 v18, v50
	s_waitcnt vmcnt(8)
	ds_write_b32 v20, v51
	s_add_i32 s16, s11, 16
	s_add_i32 s14, s10, 16
	v_or_b32_e32 v22, s16, v2
	v_or_b32_e32 v17, s14, v3
	v_mad_u64_u32 v[18:19], s[98:99], v22, s83, v[6:7]
	v_mad_u64_u32 v[20:21], s[98:99], v17, s83, v[6:7]
	s_waitcnt vmcnt(7)
	ds_write_b32 v18, v52
	s_waitcnt vmcnt(6)
	ds_write_b32 v20, v53
	s_add_i32 s16, s11, 20
	s_add_i32 s14, s10, 20
	v_or_b32_e32 v22, s16, v2
	v_or_b32_e32 v17, s14, v3
	v_mad_u64_u32 v[18:19], s[98:99], v22, s83, v[6:7]
	v_mad_u64_u32 v[20:21], s[98:99], v17, s83, v[6:7]
	s_waitcnt vmcnt(5)
	ds_write_b32 v18, v54
	s_waitcnt vmcnt(4)
	ds_write_b32 v20, v55
	s_add_i32 s16, s11, 24
	s_add_i32 s14, s10, 24
	v_or_b32_e32 v22, s16, v2
	v_or_b32_e32 v17, s14, v3
	v_mad_u64_u32 v[18:19], s[98:99], v22, s83, v[6:7]
	v_mad_u64_u32 v[20:21], s[98:99], v17, s83, v[6:7]
	s_waitcnt vmcnt(3)
	ds_write_b32 v18, v56
	s_waitcnt vmcnt(2)
	ds_write_b32 v20, v57
	s_add_i32 s16, s11, 28
	s_add_i32 s14, s10, 28
	v_or_b32_e32 v22, s16, v2
	v_or_b32_e32 v17, s14, v3
	v_mad_u64_u32 v[18:19], s[98:99], v22, s83, v[6:7]
	v_mad_u64_u32 v[20:21], s[98:99], v17, s83, v[6:7]
	s_waitcnt vmcnt(1)
	ds_write_b32 v18, v58
	s_waitcnt vmcnt(0)
	ds_write_b32 v20, v59
	s_cmp_lg_u32 s7, 0
	s_cbranch_scc1 .LBB0_263
; #define LAS __attribute__((address_space(3)))
; __device__ __forceinline__ unsigned pkbf(float lo, float hi) { f32x2 v = {lo, hi}; bf16x2v b = __builtin_convertvector(v, bf16x2v); return __builtin_bit_cast(unsigned, b); }
; template <int MODE> __device__ __forceinline__ void transpose_item(const float* W, int K, int N, bf16_t* WT, LAS float* scr, int item, int lane) {
;     ...
;     asm volatile("s_waitcnt lgkmcnt(0)" ::: "memory");
;     const int c = lane & 7;
; #pragma unroll
;     for (int j = 0; j < 4; ++j) {
;         const int n = (lane >> 3) + 8 * j, gn = n0 + n; const LAS float* s = scr + (8 * c) * 33 + n;
;         const int drow = MODE == 0 ? gn : (MODE == 1 ? (gn >= 8608 ? gn + 96 : gn) : (gn < DFF ? 2 * gn : 2 * (gn - DFF) + 1));
;         u32x4 o; o.x = pkbf(s[0 * 33], s[1 * 33]); o.y = pkbf(s[2 * 33], s[3 * 33]); o.z = pkbf(s[4 * 33], s[5 * 33]); o.w = pkbf(s[6 * 33], s[7 * 33]);
;         *(u32x4*)(WT + (size_t)drow * K + k0 + 8 * c) = o;
;     }
;     asm volatile("s_waitcnt lgkmcnt(0)" ::: "memory");
; }
	s_waitcnt lgkmcnt(0)
	v_or_b32_e32 v0, s40, v12
	ds_read2_b32 v[24:25], v13 offset0:33 offset1:41
	ds_read2_b32 v[26:27], v13 offset1:8
	ds_read2_b32 v[28:29], v13 offset0:66 offset1:74
	ds_read2_b32 v[30:31], v13 offset0:99 offset1:107
	ds_read2_b32 v[32:33], v13 offset0:132 offset1:140
	ds_read2_b32 v[34:35], v13 offset0:165 offset1:173
	ds_read2_b32 v[36:37], v13 offset0:198 offset1:206
	ds_read2_b32 v[38:39], v13 offset0:231 offset1:239
	v_cmp_lt_i32_e32 vcc, s9, v0
	v_add_u32_e32 v7, 0x60, v0
	s_ashr_i32 s43, s42, 31
	v_cndmask_b32_e32 v22, v0, v7, vcc
	v_ashrrev_i32_e32 v23, 31, v22
	v_lshl_add_u64 v[10:11], s[42:43], 1, v[8:9]
	v_lshlrev_b64 v[22:23], 11, v[22:23]
	v_or_b32_e32 v0, s40, v14
	s_waitcnt lgkmcnt(6)
	v_cvt_pk_bf16_f32 v18, v26, v24
	s_waitcnt lgkmcnt(4)
	v_cvt_pk_bf16_f32 v19, v28, v30
	s_waitcnt lgkmcnt(2)
	v_cvt_pk_bf16_f32 v20, v32, v34
	s_waitcnt lgkmcnt(0)
	v_cvt_pk_bf16_f32 v21, v36, v38
	v_lshl_add_u64 v[22:23], v[10:11], 0, v[22:23]
	v_cmp_lt_i32_e32 vcc, s9, v0
	v_add_u32_e32 v7, 0x60, v0
	global_store_dwordx4 v[22:23], v[18:21], off
	v_cndmask_b32_e32 v22, v0, v7, vcc
	v_ashrrev_i32_e32 v23, 31, v22
	v_lshlrev_b64 v[22:23], 11, v[22:23]
	v_cvt_pk_bf16_f32 v18, v27, v25
	v_cvt_pk_bf16_f32 v19, v29, v31
	v_cvt_pk_bf16_f32 v20, v33, v35
	v_cvt_pk_bf16_f32 v21, v37, v39
	v_lshl_add_u64 v[22:23], v[10:11], 0, v[22:23]
	global_store_dwordx4 v[22:23], v[18:21], off
	v_or_b32_e32 v0, s40, v15
	ds_read2_b32 v[24:25], v13 offset0:49 offset1:57
	ds_read2_b32 v[26:27], v13 offset0:16 offset1:24
	ds_read2_b32 v[28:29], v13 offset0:82 offset1:90
	ds_read2_b32 v[30:31], v13 offset0:115 offset1:123
	ds_read2_b32 v[32:33], v13 offset0:148 offset1:156
	ds_read2_b32 v[34:35], v13 offset0:181 offset1:189
	ds_read2_b32 v[36:37], v13 offset0:214 offset1:222
	ds_read2_b32 v[38:39], v13 offset0:247 offset1:255
	v_cmp_lt_i32_e32 vcc, s9, v0
	v_add_u32_e32 v7, 0x60, v0
	s_waitcnt lgkmcnt(6)
	v_cvt_pk_bf16_f32 v18, v26, v24
	v_cndmask_b32_e32 v22, v0, v7, vcc
	v_ashrrev_i32_e32 v23, 31, v22
	v_lshlrev_b64 v[22:23], 11, v[22:23]
	v_or_b32_e32 v0, s40, v16
	s_waitcnt lgkmcnt(4)
	v_cvt_pk_bf16_f32 v19, v28, v30
	s_waitcnt lgkmcnt(2)
	v_cvt_pk_bf16_f32 v20, v32, v34
	s_waitcnt lgkmcnt(0)
	v_cvt_pk_bf16_f32 v21, v36, v38
	v_lshl_add_u64 v[22:23], v[10:11], 0, v[22:23]
	v_cmp_lt_i32_e32 vcc, s9, v0
	v_add_u32_e32 v7, 0x60, v0
	global_store_dwordx4 v[22:23], v[18:21], off
	v_cndmask_b32_e32 v22, v0, v7, vcc
	v_ashrrev_i32_e32 v23, 31, v22
	v_lshlrev_b64 v[22:23], 11, v[22:23]
	v_cvt_pk_bf16_f32 v18, v27, v25
	v_cvt_pk_bf16_f32 v19, v29, v31
	v_cvt_pk_bf16_f32 v20, v33, v35
	v_cvt_pk_bf16_f32 v21, v37, v39
	v_lshl_add_u64 v[10:11], v[10:11], 0, v[22:23]
	global_store_dwordx4 v[10:11], v[18:21], off
	s_waitcnt lgkmcnt(0)
	s_add_i32 s4, s4, s1
	s_cmpk_lt_i32 s4, 0x16d0
	s_cbranch_scc1 .LBB0_262
